# attention: per-XCD work queues keyed by workgroup id mod 8 (4 balanced (batch,head) KV streams per XCD, interleaved, steal when exhausted)
# speedup vs baseline: 1.0086x; 1.0058x over previous
.LBB0_227:
	s_add_u32 s0, s16, s6
	s_addc_u32 s1, s17, s7
	global_load_dwordx4 v[4:7], v3, s[0:1]
	global_load_dwordx4 v[8:11], v3, s[0:1] offset:16
	s_add_u32 s0, s18, s6
	s_addc_u32 s1, s19, s7
	global_load_dwordx4 v[12:15], v3, s[0:1]
	global_load_dwordx4 v[16:19], v3, s[0:1] offset:16
	s_add_u32 s0, s20, s6
	s_addc_u32 s1, s21, s7
	global_load_dwordx4 v[20:23], v3, s[0:1]
	global_load_dwordx4 v[24:27], v3, s[0:1] offset:16
	s_add_u32 s0, s22, s6
	s_addc_u32 s1, s23, s7
	global_load_dwordx4 v[28:31], v3, s[0:1]
	global_load_dwordx4 v[32:35], v3, s[0:1] offset:16
	s_add_u32 s6, s6, 32
	s_addc_u32 s7, s7, 0
	s_cmpk_eq_i32 s6, 0x100
	s_waitcnt vmcnt(7)
	v_mov_b32_e32 v36, v4
	v_mov_b32_e32 v4, v6
	s_waitcnt vmcnt(6)
	v_mov_b32_e32 v6, v8
	v_mov_b32_e32 v8, v10
	s_waitcnt vmcnt(5)
	v_mov_b32_e32 v10, v12
	v_mov_b32_e32 v12, v14
	s_waitcnt vmcnt(3)
	v_mov_b32_e32 v37, v20
	v_mov_b32_e32 v20, v5
	v_mov_b32_e32 v5, v22
	v_mov_b32_e32 v22, v7
	s_waitcnt vmcnt(2)
	v_mov_b32_e32 v7, v24
	v_mov_b32_e32 v24, v9
	v_mov_b32_e32 v9, v26
	v_mov_b32_e32 v26, v11
	s_waitcnt vmcnt(1)
	v_mov_b32_e32 v11, v28
	v_mov_b32_e32 v28, v13
	v_pk_fma_f32 v[0:1], v[36:37], v[10:11], v[0:1]
	v_mov_b32_e32 v13, v30
	v_pk_fma_f32 v[0:1], v[20:21], v[28:29], v[0:1]
	v_mov_b32_e32 v30, v15
	v_pk_fma_f32 v[0:1], v[4:5], v[12:13], v[0:1]
	v_mov_b32_e32 v14, v16
	s_waitcnt vmcnt(0)
	v_mov_b32_e32 v15, v32
	v_pk_fma_f32 v[0:1], v[22:23], v[30:31], v[0:1]
	v_mov_b32_e32 v32, v17
	v_pk_fma_f32 v[0:1], v[6:7], v[14:15], v[0:1]
	v_mov_b32_e32 v16, v18
	v_mov_b32_e32 v17, v34
	v_pk_fma_f32 v[0:1], v[24:25], v[32:33], v[0:1]
	v_mov_b32_e32 v34, v19
	v_pk_fma_f32 v[0:1], v[8:9], v[16:17], v[0:1]
	s_nop 0
	v_pk_fma_f32 v[0:1], v[26:27], v[34:35], v[0:1]
	s_cbranch_scc0 .LBB0_227
	v_readlane_b32 s15, v255, 0
	v_readlane_b32 s0, v255, 1
	s_lshr_b32 s1, s15, 7
	s_bfe_u32 s16, s15, 0x10006
	v_add_u32_e32 v3, s0, v2
	s_lshl_b32 s0, s1, 14
	s_add_i32 s4, s0, 0
	s_add_u32 s42, s34, 0x20000
	s_addc_u32 s43, s35, 0
	s_lshl_b32 s5, s1, 5
	s_lshl_b32 s0, s16, 6
	v_and_b32_e32 v9, 63, v2
	v_writelane_b32 v255, s1, 30
	s_cmpk_lt_u32 s15, 0x80
	v_writelane_b32 v255, s0, 31
	s_cselect_b64 s[48:49], -1, 0
	s_add_i32 s0, 0, 0x1bc00
	v_lshlrev_b32_e32 v96, 3, v9
	v_lshlrev_b32_e32 v5, 1, v2
	v_lshrrev_b32_e32 v4, 1, v2
	v_add_u32_e32 v12, s0, v96
	v_readlane_b32 s0, v255, 2
	v_and_b32_e32 v6, 8, v5
	v_and_b32_e32 v4, 4, v4
	v_and_b32_e32 v11, 19, v2
	s_lshl_b32 s12, s0, 9
	s_add_i32 s0, 0, 0x11c00
	s_add_i32 s13, 0, 0x1c040
	v_or3_b32 v11, v6, v11, v4
	v_and_b32_e32 v6, 15, v2
	s_cmpk_gt_u32 s15, 0xff
	v_lshrrev_b32_e32 v7, 2, v2
	v_and_b32_e32 v8, 31, v2
	v_bfe_u32 v10, v2, 5, 1
	v_lshlrev_b32_e32 v4, 3, v6
	v_lshlrev_b32_e32 v6, 4, v6
	s_cselect_b64 s[50:51], -1, 0
	s_cmpk_lt_u32 s15, 0x100
	v_lshlrev_b32_e32 v2, 3, v2
	v_cmp_gt_u32_e64 s[18:19], 2, v9
	v_mul_f32_e32 v0, 0x3fb8aa3b, v0
	v_mul_f32_e32 v1, 0x3fb8aa3b, v1
	v_ashrrev_i32_e32 v140, 4, v3
	v_add_u32_e32 v13, s0, v6
	s_cselect_b64 s[28:29], -1, 0
	s_movk_i32 s0, 0x110
	v_and_b32_e32 v2, 24, v2
	v_writelane_b32 v255, s18, 32
	v_exp_f32_e32 v0, v0
	v_exp_f32_e32 v1, v1
	v_and_or_b32 v189, v5, 32, v2
	v_mul_lo_u32 v5, v140, s0
	s_and_b64 s[0:1], s[28:29], exec
	v_writelane_b32 v255, s19, 33
	v_cmp_gt_u32_e64 s[18:19], 4, v9
	s_cselect_b32 s0, 0, 32
	s_and_b32 s1, 64, s15
	v_writelane_b32 v255, s18, 34
	s_cmp_eq_u32 s16, 0
	s_cselect_b64 s[52:53], -1, 0
	v_writelane_b32 v255, s19, 35
	v_cmp_gt_u32_e64 s[18:19], 8, v9
	s_cmp_lg_u32 s1, 0
	v_sub_f32_e32 v0, v0, v1
	v_writelane_b32 v255, s18, 36
	v_add_u32_e32 v187, 0, v6
	v_cvt_f32_ubyte0_e32 v14, v11
	s_cselect_b64 s[66:67], -1, 0
	v_writelane_b32 v255, s19, 37
	v_cmp_gt_u32_e64 s[18:19], 16, v9
	s_add_u32 s27, s62, 0x10000000
	v_add_f32_e32 v147, 0x3e4ccccd, v0
	v_lshlrev_b32_e32 v0, 3, v10
	v_cvt_pk_bf16_f32 v14, v14, v14
	v_cmp_gt_u32_e64 s[10:11], 32, v9
	v_writelane_b32 v255, s18, 38
	s_addc_u32 s76, s63, 0
	s_add_i32 s77, s13, s0
	s_lshl_b32 s0, s89, 2
	v_add_u32_e32 v146, v187, v5
	v_mov_b32_e32 v97, 0
	v_cndmask_b32_e64 v100, 0, v14, s[10:11]
	v_mul_u32_u24_e32 v14, 0x110, v11
	v_or_b32_e32 v11, 32, v11
	v_and_or_b32 v7, v7, 3, v0
	s_movk_i32 s14, 0x140
	v_writelane_b32 v255, s19, 39
	s_add_i32 s77, s77, s0
	v_mad_u64_u32 v[148:149], s[0:1], v140, 48, v[146:147]
	v_lshlrev_b32_e32 v1, 2, v8
	v_lshlrev_b32_e32 v6, 4, v10
	v_cvt_f32_ubyte0_e32 v11, v11
	v_lshlrev_b32_e32 v2, 9, v10
	v_mad_u32_u24 v192, v7, s14, 0
	v_mov_b32_e32 v7, v97
	v_writelane_b32 v255, s16, 40
	s_lshl_b32 s0, s16, 9
	v_cmp_eq_u32_e64 s[22:23], 0, v3
	v_or_b32_e32 v186, s5, v8
	v_cmp_gt_i32_e64 s[8:9], 4, v3
	v_lshl_add_u32 v188, v3, 2, s13
	v_lshl_or_b32 v3, s16, 7, v6
	v_cvt_pk_bf16_f32 v11, v11, v11
	v_mul_lo_u32 v190, v140, s14
	v_add3_u32 v191, s4, v1, v2
	v_lshlrev_b32_e32 v2, 2, v10
	v_lshl_add_u64 v[144:145], s[24:25], 0, v[6:7]
	s_add_i32 s78, s0, 0
	v_sub_u32_e32 v1, v0, v8
	v_readlane_b32 s0, v255, 24
	s_mov_b32 s24, 1.0
	s_mov_b32 s41, 0
	v_ashrrev_i32_e32 v141, 31, v140
	v_cmp_eq_u32_e64 s[6:7], 0, v9
	v_mov_b32_e32 v101, v97
	v_mov_b32_e32 v102, v97
	v_mov_b32_e32 v103, v97
	v_cndmask_b32_e64 v104, 0, v11, s[10:11]
	v_mov_b32_e32 v105, v97
	v_mov_b32_e32 v106, v97
	v_mov_b32_e32 v107, v97
	v_lshl_add_u64 v[142:143], s[68:69], 0, v[96:97]
	v_add3_u32 v193, 0, v14, v3
	v_subrev_u32_e32 v149, 64, v186
	v_subrev_u32_e32 v194, s5, v1
	s_add_i32 s79, s0, -1
	s_add_i32 s72, 0, 0x1c000
	v_lshlrev_b32_e32 v150, 1, v0
	v_lshlrev_b32_e32 v152, 1, v4
	s_mov_b32 s80, 0xf800000
	v_mov_b32_e32 v195, 0x260
	v_add_u32_e32 v196, s12, v12
	v_add_u32_e32 v197, v13, v190
	s_mov_b32 s25, 0xc3200000
	v_lshlrev_b32_e32 v154, 1, v2
	v_mov_b32_e32 v198, 0x3727c5ac
	v_mbcnt_hi_u32_b32 v254, -1, v139
	v_mov_b32_e32 v199, 0x42800000
	s_mov_b32 s101, s2
	s_mov_b32 s100, 0
	s_and_b32 s101, s101, 7
	s_branch .LBB0_231

.Lattn_q_retry:
	s_cmp_gt_u32 s100, 7
	s_cbranch_scc1 .Lattn_q_none
	s_add_i32 s0, s101, s100
	s_and_b32 s0, s0, 7
	s_lshl_b32 s68, s0, 6
	v_mov_b32_e32 v0, s68
	v_mov_b32_e32 v1, 1
	global_atomic_add v1, v0, v1, s[42:43] sc0
	s_waitcnt vmcnt(0)
	v_readfirstlane_b32 s69, v1
	s_nop 3
	s_cmp_lt_u32 s69, 0x100
	s_cbranch_scc1 .Lattn_q_got
	s_add_i32 s100, s100, 1
	s_branch .Lattn_q_retry
.Lattn_q_got:
	s_and_b32 s68, s69, 3
	s_lshl_b32 s68, s68, 2
	s_movk_i32 s70, 0x257
	s_movk_i32 s71, 0x1346
	s_bitcmp1_b32 s0, 0
	s_cselect_b32 s70, s71, s70
	s_lshr_b32 s70, s70, s68
	s_and_b32 s70, s70, 7
	s_lshr_b32 s68, s0, 1
	s_lshl_b32 s68, s68, 3
	s_or_b32 s70, s70, s68
	s_lshr_b32 s69, s69, 2
	s_lshl_b32 s69, s69, 5
	s_or_b32 s0, s69, s70
	s_branch .Lattn_q_put
.Lattn_q_none:
	s_movk_i32 s0, 0x800
.Lattn_q_put:
	v_mov_b32_e32 v1, s72
	v_mov_b32_e32 v0, s0
	ds_write_b32 v1, v0
